# final-norm loop: all x/gain chunk loads of a row hoisted with counted vmcnt waits; plus x-rows hoist, hand-written prep conversion, LDS-staged S5 carry scan
# baseline (speedup 1.0000x reference)
; __device__ __forceinline__ float bf_lo(unsigned w) { return __uint_as_float(w << 16); }
; __device__ __forceinline__ float bf_hi(unsigned w) { return __uint_as_float(w & 0xffff0000u); }
; __device__ __forceinline__ float row_rstd(const float* ssqp, int row) {
;     const f32x4* p = (const f32x4*)(ssqp + (size_t)row * 32); f32x4 a = p[0];
; #pragma unroll
;     for (int i = 1; i < 8; ++i) a += p[i];
;     return rsqrtf(((a[0] + a[1]) + (a[2] + a[3])) * (1.0f / DM) + RMS_EPS);
; }
; __global__ void __launch_bounds__(NTHR) hybrid_encoder_fwd(Params P) {
;     ...
;         const float* ssq = SSQ + (size_t)8 * SEQ * 32; const float* gf = P.in[20];
;         for (int row = bid * 8 + wid; row < SEQ; row += G * 8) {
;             const float rs = row_rstd(ssq, row);
; #pragma unroll
;             for (int i = 0; i < 8; ++i) { const int c = lane * 4 + 256 * i;
;                 const u32x2 xw = *(const u32x2*)(XG + (size_t)row * DM + c); const f32x4 gv = *(const f32x4*)(gf + c);
;                 f32x4 v; v[0] = bf_lo(xw.x); v[1] = bf_hi(xw.x); v[2] = bf_lo(xw.y); v[3] = bf_hi(xw.y);
;                 *(f32x4*)(P.out + (size_t)row * DM + c) = v * rs * gv; }
;         }
.LBB0_972:
	s_add_u32 s10, s96, s2
	v_lshl_add_u64 v[16:17], s[96:97], 0, v[10:11]
	s_addc_u32 s11, s97, s3
	v_add_co_u32_e32 v52, vcc, s9, v16
	s_add_u32 s12, s10, 0x39584000
	s_nop 0
	v_addc_co_u32_e32 v53, vcc, 0, v17, vcc
	global_load_dwordx4 v[16:19], v14, s[10:11]
	global_load_dwordx4 v[20:23], v14, s[10:11] offset:64
	s_addc_u32 s13, s11, 0
	global_load_dwordx4 v[24:27], v155, s[12:13] offset:16
	global_load_dwordx2 v[54:55], v[52:53], off
	global_load_dwordx4 v[28:31], v155, s[12:13] offset:32
	global_load_dwordx4 v[32:35], v155, s[12:13] offset:48
	s_add_u32 s10, s10, 0x39584040
	s_addc_u32 s11, s11, 0
	global_load_dwordx4 v[36:39], v155, s[10:11] offset:16
	global_load_dwordx4 v[40:43], v155, s[10:11] offset:32
	global_load_dwordx4 v[44:47], v155, s[10:11] offset:48
	global_load_dwordx4 v[48:51], v[0:1], off
	global_load_dwordx2 v[60:61], v[52:53], off offset:512
	global_load_dwordx4 v[76:79], v[0:1], off offset:1024
	global_load_dwordx2 v[62:63], v[52:53], off offset:1024
	global_load_dwordx4 v[80:83], v[0:1], off offset:2048
	global_load_dwordx2 v[64:65], v[52:53], off offset:1536
	global_load_dwordx4 v[84:87], v[0:1], off offset:3072
	global_load_dwordx2 v[66:67], v[52:53], off offset:2048
	global_load_dwordx4 v[88:91], v[2:3], off
	global_load_dwordx2 v[68:69], v[52:53], off offset:2560
	global_load_dwordx4 v[92:95], v[4:5], off
	global_load_dwordx2 v[70:71], v[52:53], off offset:3072
	global_load_dwordx4 v[96:99], v[6:7], off
	global_load_dwordx2 v[72:73], v[52:53], off offset:3584
	global_load_dwordx4 v[100:103], v[8:9], off
	s_add_i32 s14, s14, s16
	s_add_u32 s2, s2, s4
	s_addc_u32 s3, s3, s5
	v_lshl_add_u64 v[10:11], v[10:11], 0, s[0:1]
	s_cmpk_gt_i32 s14, 0x1fff
	s_waitcnt vmcnt(21)
	v_pk_add_f32 v[18:19], v[18:19], v[26:27]
	v_pk_add_f32 v[16:17], v[16:17], v[24:25]
	s_waitcnt vmcnt(19)
	v_pk_add_f32 v[18:19], v[18:19], v[30:31]
	v_pk_add_f32 v[16:17], v[16:17], v[28:29]
	s_waitcnt vmcnt(18)
	v_pk_add_f32 v[18:19], v[18:19], v[34:35]
	v_pk_add_f32 v[16:17], v[16:17], v[32:33]
	v_pk_add_f32 v[18:19], v[18:19], v[22:23]
	v_pk_add_f32 v[16:17], v[16:17], v[20:21]
	s_waitcnt vmcnt(17)
	v_pk_add_f32 v[18:19], v[18:19], v[38:39]
	v_pk_add_f32 v[16:17], v[16:17], v[36:37]
	s_waitcnt vmcnt(16)
	v_pk_add_f32 v[18:19], v[18:19], v[42:43]
	v_pk_add_f32 v[16:17], v[16:17], v[40:41]
	s_waitcnt vmcnt(15)
	v_pk_add_f32 v[18:19], v[18:19], v[46:47]
	v_pk_add_f32 v[16:17], v[16:17], v[44:45]
	v_mov_b32_e32 v21, v18
	v_mov_b32_e32 v20, v17
	v_mov_b32_e32 v17, v19
	v_pk_add_f32 v[16:17], v[20:21], v[16:17]
	v_lshlrev_b32_e32 v24, 16, v54
	v_add_f32_e32 v16, v16, v17
	v_fmamk_f32 v16, v16, 0x3a000000, v15
	v_mul_f32_e32 v17, 0x4b800000, v16
	v_cmp_gt_f32_e32 vcc, s8, v16
	v_and_b32_e32 v25, 0xffff0000, v54
	v_lshlrev_b32_e32 v26, 16, v55
	v_cndmask_b32_e32 v16, v16, v17, vcc
	v_rsq_f32_e32 v16, v16
	v_and_b32_e32 v27, 0xffff0000, v55
	v_mul_f32_e32 v17, 0x45800000, v16
	v_cndmask_b32_e32 v20, v16, v17, vcc
	v_pk_mul_f32 v[16:17], v[20:21], v[24:25] op_sel_hi:[0,1]
	v_pk_mul_f32 v[18:19], v[20:21], v[26:27] op_sel_hi:[0,1]
	s_waitcnt vmcnt(14)
	v_pk_mul_f32 v[18:19], v[50:51], v[18:19]
	v_pk_mul_f32 v[16:17], v[48:49], v[16:17]
	global_store_dwordx4 v[12:13], v[16:19], off offset:-4096
	s_waitcnt vmcnt(13)
	v_lshlrev_b32_e32 v24, 16, v60
	v_and_b32_e32 v25, 0xffff0000, v60
	v_lshlrev_b32_e32 v22, 16, v61
	v_and_b32_e32 v23, 0xffff0000, v61
	v_pk_mul_f32 v[24:25], v[20:21], v[24:25] op_sel_hi:[0,1]
	v_pk_mul_f32 v[22:23], v[20:21], v[22:23] op_sel_hi:[0,1]
	s_waitcnt vmcnt(13)
	v_pk_mul_f32 v[18:19], v[78:79], v[22:23]
	v_pk_mul_f32 v[16:17], v[76:77], v[24:25]
	global_store_dwordx4 v[12:13], v[16:19], off offset:-3072
	s_waitcnt vmcnt(12)
	v_lshlrev_b32_e32 v24, 16, v62
	v_and_b32_e32 v25, 0xffff0000, v62
	v_lshlrev_b32_e32 v22, 16, v63
	v_and_b32_e32 v23, 0xffff0000, v63
	v_pk_mul_f32 v[24:25], v[20:21], v[24:25] op_sel_hi:[0,1]
	v_pk_mul_f32 v[22:23], v[20:21], v[22:23] op_sel_hi:[0,1]
	s_waitcnt vmcnt(12)
	v_pk_mul_f32 v[18:19], v[82:83], v[22:23]
	v_pk_mul_f32 v[16:17], v[80:81], v[24:25]
	global_store_dwordx4 v[12:13], v[16:19], off offset:-2048
	s_waitcnt vmcnt(11)
	v_lshlrev_b32_e32 v24, 16, v64
	v_and_b32_e32 v25, 0xffff0000, v64
	v_lshlrev_b32_e32 v22, 16, v65
	v_and_b32_e32 v23, 0xffff0000, v65
	v_pk_mul_f32 v[24:25], v[20:21], v[24:25] op_sel_hi:[0,1]
	v_pk_mul_f32 v[22:23], v[20:21], v[22:23] op_sel_hi:[0,1]
	s_waitcnt vmcnt(11)
	v_pk_mul_f32 v[18:19], v[86:87], v[22:23]
	v_pk_mul_f32 v[16:17], v[84:85], v[24:25]
	global_store_dwordx4 v[12:13], v[16:19], off offset:-1024
	s_waitcnt vmcnt(10)
	v_lshlrev_b32_e32 v24, 16, v66
	v_and_b32_e32 v25, 0xffff0000, v66
	v_lshlrev_b32_e32 v22, 16, v67
	v_and_b32_e32 v23, 0xffff0000, v67
	v_pk_mul_f32 v[24:25], v[20:21], v[24:25] op_sel_hi:[0,1]
	v_pk_mul_f32 v[22:23], v[20:21], v[22:23] op_sel_hi:[0,1]
	s_waitcnt vmcnt(10)
	v_pk_mul_f32 v[18:19], v[90:91], v[22:23]
	v_pk_mul_f32 v[16:17], v[88:89], v[24:25]
	global_store_dwordx4 v[12:13], v[16:19], off
	s_waitcnt vmcnt(9)
	v_lshlrev_b32_e32 v24, 16, v68
	v_and_b32_e32 v25, 0xffff0000, v68
	v_lshlrev_b32_e32 v22, 16, v69
	v_and_b32_e32 v23, 0xffff0000, v69
	v_pk_mul_f32 v[24:25], v[20:21], v[24:25] op_sel_hi:[0,1]
	v_pk_mul_f32 v[22:23], v[20:21], v[22:23] op_sel_hi:[0,1]
	s_waitcnt vmcnt(9)
	v_pk_mul_f32 v[18:19], v[94:95], v[22:23]
	v_pk_mul_f32 v[16:17], v[92:93], v[24:25]
	global_store_dwordx4 v[12:13], v[16:19], off offset:1024
	s_waitcnt vmcnt(8)
	v_lshlrev_b32_e32 v24, 16, v70
	v_and_b32_e32 v25, 0xffff0000, v70
	v_lshlrev_b32_e32 v22, 16, v71
	v_and_b32_e32 v23, 0xffff0000, v71
	v_pk_mul_f32 v[24:25], v[20:21], v[24:25] op_sel_hi:[0,1]
	v_pk_mul_f32 v[22:23], v[20:21], v[22:23] op_sel_hi:[0,1]
	s_waitcnt vmcnt(8)
	v_pk_mul_f32 v[18:19], v[98:99], v[22:23]
	v_pk_mul_f32 v[16:17], v[96:97], v[24:25]
	global_store_dwordx4 v[12:13], v[16:19], off offset:2048
	s_waitcnt vmcnt(7)
	v_lshlrev_b32_e32 v24, 16, v72
	v_and_b32_e32 v25, 0xffff0000, v72
	v_lshlrev_b32_e32 v22, 16, v73
	v_and_b32_e32 v23, 0xffff0000, v73
	v_pk_mul_f32 v[24:25], v[20:21], v[24:25] op_sel_hi:[0,1]
	v_pk_mul_f32 v[20:21], v[20:21], v[22:23] op_sel_hi:[0,1]
	s_waitcnt vmcnt(7)
	v_pk_mul_f32 v[18:19], v[102:103], v[20:21]
	v_pk_mul_f32 v[16:17], v[100:101], v[24:25]
	global_store_dwordx4 v[12:13], v[16:19], off offset:3072
	v_lshl_add_u64 v[12:13], v[12:13], 0, s[6:7]
	s_cbranch_scc0 .LBB0_972
